# hook entry drains to vmcnt(8) instead of vmcnt(0): the preceding epilogue's last row-sum atomics / stores stay in flight under the first weight loads
# speedup vs baseline: 1.0052x; 1.0003x over previous
; #define lane lane_id()
; __device__ __forceinline__ void conv_load4(const float* __restrict__ W, int N, int item, int lane, f32x4 (&x)[16]) {
;     const int nblk = N / 64, k0 = 64 * (item / nblk), n0 = 64 * (item % nblk);
; #pragma unroll
;     for (int i = 0; i < 16; ++i) x[i] = __builtin_nontemporal_load((const f32x4*)(W + (size_t)(k0 + 4 * i + (lane >> 4)) * N + n0 + 4 * (lane & 15)));
; }
;     __device__ __forceinline__ void done(const Unit&) const {
;         constexpr int I2 = (GW / 64) * (DM / 64), I3 = (DM / 64) * (4 * DM / 64), I4 = (DM / 64) * (DM / 64);
;         const int u = n_done++;
;     ...
;         f32x4 va[16];
;         if (u == 0 || u == 1) { for (int it = gw + u * ngw; it < I3; it += 2 * ngw) { conv_load4(w3, 4 * DM, it, ln, va); conv_xpose(va, ln); conv_store4(DM, 4 * DM, t3, it, ln, g1, va); } }
;         else if (u == 2) { for (int it = gw; it < I2; it += ngw) { conv_load4(w2, DM, it, ln, va); conv_xpose(va, ln); conv_store4(GW, DM, t2, it, ln, nullptr, va); } }
;         else if (u == 3) { for (int it = gw; it < I4; it += ngw) { conv_load4(w4, DM, it, ln, va); conv_xpose(va, ln); conv_store4(DM, DM, t4, it, ln, nullptr, va); } }
;     ...
;         if (u != trigger) return;
;         f32x4 va[16], vb[16];
;         for (int it = gw; it < I3; it += 2 * ngw) {
;             const bool two = it + ngw < I3;
;             conv_load4(w3, 4 * DM, it, ln, va); if (two) conv_load4(w3, 4 * DM, it + ngw, ln, vb);
.LBB0_153:
	s_cmpk_lg_u32 s63, 0x1000
	s_cbranch_scc1 .Lhk_generic
	s_waitcnt lgkmcnt(0)
	v_add_u32_e32 v246, v198, v199
	v_add_u32_e32 v247, v198, v201
	s_waitcnt vmcnt(8)
	s_mov_b32 s37, s96
	s_lshr_b32 s18, s37, 7
	s_lshl_b32 s18, s18, 6
	s_and_b32 s19, s37, 127
	s_lshl_b32 s19, s19, 6
	s_lshl_b32 s49, s19, 12
	s_lshl_b32 s50, s18, 1
	s_add_i32 s24, s49, s50
	v_add_u32_e32 v240, s18, v153
	v_mov_b32_e32 v241, 0
	v_lshlrev_b64 v[240:241], 15, v[240:241]
	s_lshl_b32 s100, s19, 2
	s_mov_b32 s101, 0
	v_lshl_add_u64 v[238:239], s[100:101], 0, v[136:137]
	v_lshl_add_u64 v[238:239], v[238:239], 0, v[240:241]
	s_mov_b32 s46, 0x20000
	s_mov_b32 s47, 0
	global_load_dwordx4 v[0:3], v[238:239], off nt
	v_lshl_add_u64 v[238:239], v[238:239], 0, s[46:47]
	global_load_dwordx4 v[4:7], v[238:239], off nt
	v_lshl_add_u64 v[238:239], v[238:239], 0, s[46:47]
	global_load_dwordx4 v[8:11], v[238:239], off nt
	v_lshl_add_u64 v[238:239], v[238:239], 0, s[46:47]
	global_load_dwordx4 v[12:15], v[238:239], off nt
	v_lshl_add_u64 v[238:239], v[238:239], 0, s[46:47]
	global_load_dwordx4 v[16:19], v[238:239], off nt
	v_lshl_add_u64 v[238:239], v[238:239], 0, s[46:47]
	global_load_dwordx4 v[20:23], v[238:239], off nt
	v_lshl_add_u64 v[238:239], v[238:239], 0, s[46:47]
	global_load_dwordx4 v[24:27], v[238:239], off nt
	v_lshl_add_u64 v[238:239], v[238:239], 0, s[46:47]
	global_load_dwordx4 v[28:31], v[238:239], off nt
	v_lshl_add_u64 v[238:239], v[238:239], 0, s[46:47]
	global_load_dwordx4 v[32:35], v[238:239], off nt
	v_lshl_add_u64 v[238:239], v[238:239], 0, s[46:47]
	global_load_dwordx4 v[36:39], v[238:239], off nt
	v_lshl_add_u64 v[238:239], v[238:239], 0, s[46:47]
	global_load_dwordx4 v[40:43], v[238:239], off nt
	v_lshl_add_u64 v[238:239], v[238:239], 0, s[46:47]
	global_load_dwordx4 v[44:47], v[238:239], off nt
	v_lshl_add_u64 v[238:239], v[238:239], 0, s[46:47]
	global_load_dwordx4 v[48:51], v[238:239], off nt
	v_lshl_add_u64 v[238:239], v[238:239], 0, s[46:47]
	global_load_dwordx4 v[52:55], v[238:239], off nt
	v_lshl_add_u64 v[238:239], v[238:239], 0, s[46:47]
	global_load_dwordx4 v[56:59], v[238:239], off nt
	v_lshl_add_u64 v[238:239], v[238:239], 0, s[46:47]
	global_load_dwordx4 v[60:63], v[238:239], off nt
	s_lshl_b32 s50, s18, 2
	s_add_u32 s98, s57, s50
	s_addc_u32 s99, s58, 0
	v_lshlrev_b32_e32 v242, 2, v153
	global_load_dword v158, v242, s[98:99]
	global_load_dword v159, v242, s[98:99] offset:16
	global_load_dword v160, v242, s[98:99] offset:32
	global_load_dword v161, v242, s[98:99] offset:48
	global_load_dword v162, v242, s[98:99] offset:64
	global_load_dword v163, v242, s[98:99] offset:80
	global_load_dword v164, v242, s[98:99] offset:96
	global_load_dword v165, v242, s[98:99] offset:112
	global_load_dword v166, v242, s[98:99] offset:128
	global_load_dword v167, v242, s[98:99] offset:144
	global_load_dword v168, v242, s[98:99] offset:160
	global_load_dword v169, v242, s[98:99] offset:176
	global_load_dword v170, v242, s[98:99] offset:192
	global_load_dword v171, v242, s[98:99] offset:208
	global_load_dword v172, v242, s[98:99] offset:224
	global_load_dword v173, v242, s[98:99] offset:240
	s_add_i32 s37, s96, 0x800
	s_lshr_b32 s18, s37, 7
	s_lshl_b32 s18, s18, 6
	s_and_b32 s19, s37, 127
	s_lshl_b32 s19, s19, 6
	s_lshl_b32 s49, s19, 12
	s_lshl_b32 s50, s18, 1
	s_add_i32 s25, s49, s50
	v_add_u32_e32 v240, s18, v153
	v_mov_b32_e32 v241, 0
	v_lshlrev_b64 v[240:241], 15, v[240:241]
	s_lshl_b32 s100, s19, 2
	s_mov_b32 s101, 0
	v_lshl_add_u64 v[238:239], s[100:101], 0, v[136:137]
	v_lshl_add_u64 v[238:239], v[238:239], 0, v[240:241]
	s_mov_b32 s46, 0x20000
	s_mov_b32 s47, 0
	global_load_dwordx4 v[64:67], v[238:239], off nt
	v_lshl_add_u64 v[238:239], v[238:239], 0, s[46:47]
	global_load_dwordx4 v[68:71], v[238:239], off nt
	v_lshl_add_u64 v[238:239], v[238:239], 0, s[46:47]
	global_load_dwordx4 v[72:75], v[238:239], off nt
	v_lshl_add_u64 v[238:239], v[238:239], 0, s[46:47]
	global_load_dwordx4 v[76:79], v[238:239], off nt
	v_lshl_add_u64 v[238:239], v[238:239], 0, s[46:47]
	global_load_dwordx4 v[80:83], v[238:239], off nt
	v_lshl_add_u64 v[238:239], v[238:239], 0, s[46:47]
	global_load_dwordx4 v[84:87], v[238:239], off nt
	v_lshl_add_u64 v[238:239], v[238:239], 0, s[46:47]
	global_load_dwordx4 v[88:91], v[238:239], off nt
	v_lshl_add_u64 v[238:239], v[238:239], 0, s[46:47]
	global_load_dwordx4 v[92:95], v[238:239], off nt
	v_lshl_add_u64 v[238:239], v[238:239], 0, s[46:47]
	global_load_dwordx4 v[96:99], v[238:239], off nt
	v_lshl_add_u64 v[238:239], v[238:239], 0, s[46:47]
	global_load_dwordx4 v[100:103], v[238:239], off nt
	v_lshl_add_u64 v[238:239], v[238:239], 0, s[46:47]
	global_load_dwordx4 v[104:107], v[238:239], off nt
	v_lshl_add_u64 v[238:239], v[238:239], 0, s[46:47]
	global_load_dwordx4 v[108:111], v[238:239], off nt
	v_lshl_add_u64 v[238:239], v[238:239], 0, s[46:47]
	global_load_dwordx4 v[112:115], v[238:239], off nt
	v_lshl_add_u64 v[238:239], v[238:239], 0, s[46:47]
	global_load_dwordx4 v[116:119], v[238:239], off nt
	v_lshl_add_u64 v[238:239], v[238:239], 0, s[46:47]
	global_load_dwordx4 v[120:123], v[238:239], off nt
	v_lshl_add_u64 v[238:239], v[238:239], 0, s[46:47]
	global_load_dwordx4 v[124:127], v[238:239], off nt
	s_waitcnt vmcnt(16)
; __device__ __forceinline__ unsigned cvt_pk_bf16(float lo, float hi) { unsigned r; asm volatile("v_cvt_pk_bf16_f32 %0, %1, %2" : "=v"(r) : "v"(lo), "v"(hi)); return r; }
; #define lane lane_id()
; __device__ __forceinline__ void conv_xpose(f32x4 (&x)[16], int lane) {
;     const bool a = (lane >> 4) & 1, b = (lane >> 5) & 1;
; #pragma unroll
;     for (int i = 0; i < 16; ++i) {
;         f32x4 v = x[i];
;         {
;             const float s0 = a ? v[0] : v[1], s1 = a ? v[2] : v[3];
;             const float r0 = __shfl_xor(s0, 16), r1 = __shfl_xor(s1, 16);
;             if (a) { v[0] = r0; v[2] = r1; } else { v[1] = r0; v[3] = r1; }
;         }
;         {
;             const float s0 = b ? v[0] : v[2], s1 = b ? v[1] : v[3];
;             const float r0 = __shfl_xor(s0, 32), r1 = __shfl_xor(s1, 32);
;             if (b) { v[0] = r0; v[1] = r1; } else { v[2] = r0; v[3] = r1; }
;         }
;         x[i] = v;
;     }
; }
; __device__ __forceinline__ void conv_store4(int K, int N, bf16_t* __restrict__ WT, int item, int lane, const float* __restrict__ gk, const f32x4 (&x)[16]) {
;     ...
;         for (int j = 0; j < 8; ++j) g[j] = gk ? gk[k0 + 8 * kc + j] : 1.0f;
;         const f32x4 lo = x[2 * kc], hi = x[2 * kc + 1];
;         u32x4 o; o.x = cvt_pk_bf16(lo[0] * g[0], lo[1] * g[1]); o.y = cvt_pk_bf16(lo[2] * g[2], lo[3] * g[3]);
;         o.z = cvt_pk_bf16(hi[0] * g[4], hi[1] * g[5]); o.w = cvt_pk_bf16(hi[2] * g[6], hi[3] * g[7]);
	s_lshl_b32 s50, s18, 2
	s_add_u32 s98, s57, s50
	s_addc_u32 s99, s58, 0
	v_lshlrev_b32_e32 v242, 2, v153
	global_load_dword v174, v242, s[98:99]
	global_load_dword v175, v242, s[98:99] offset:16
	global_load_dword v176, v242, s[98:99] offset:32
	global_load_dword v177, v242, s[98:99] offset:48
	global_load_dword v178, v242, s[98:99] offset:64
	global_load_dword v179, v242, s[98:99] offset:80
	global_load_dword v180, v242, s[98:99] offset:96
	global_load_dword v181, v242, s[98:99] offset:112
	global_load_dword v182, v242, s[98:99] offset:128
	global_load_dword v183, v242, s[98:99] offset:144
	global_load_dword v184, v242, s[98:99] offset:160
	global_load_dword v185, v242, s[98:99] offset:176
	global_load_dword v186, v242, s[98:99] offset:192
	global_load_dword v187, v242, s[98:99] offset:208
	global_load_dword v188, v242, s[98:99] offset:224
	global_load_dword v189, v242, s[98:99] offset:240
	v_pk_mul_f32 v[0:1], v[0:1], v[158:159] op_sel_hi:[1,0]
	v_pk_mul_f32 v[2:3], v[2:3], v[158:159] op_sel_hi:[1,0]
	v_pk_mul_f32 v[4:5], v[4:5], v[158:159] op_sel:[0,1] op_sel_hi:[1,1]
	v_pk_mul_f32 v[6:7], v[6:7], v[158:159] op_sel:[0,1] op_sel_hi:[1,1]
	v_pk_mul_f32 v[8:9], v[8:9], v[160:161] op_sel_hi:[1,0]
	v_pk_mul_f32 v[10:11], v[10:11], v[160:161] op_sel_hi:[1,0]
	v_pk_mul_f32 v[12:13], v[12:13], v[160:161] op_sel:[0,1] op_sel_hi:[1,1]
	v_pk_mul_f32 v[14:15], v[14:15], v[160:161] op_sel:[0,1] op_sel_hi:[1,1]
	v_pk_mul_f32 v[16:17], v[16:17], v[162:163] op_sel_hi:[1,0]
	v_pk_mul_f32 v[18:19], v[18:19], v[162:163] op_sel_hi:[1,0]
	v_pk_mul_f32 v[20:21], v[20:21], v[162:163] op_sel:[0,1] op_sel_hi:[1,1]
	v_pk_mul_f32 v[22:23], v[22:23], v[162:163] op_sel:[0,1] op_sel_hi:[1,1]
	v_pk_mul_f32 v[24:25], v[24:25], v[164:165] op_sel_hi:[1,0]
	v_pk_mul_f32 v[26:27], v[26:27], v[164:165] op_sel_hi:[1,0]
	v_pk_mul_f32 v[28:29], v[28:29], v[164:165] op_sel:[0,1] op_sel_hi:[1,1]
	v_pk_mul_f32 v[30:31], v[30:31], v[164:165] op_sel:[0,1] op_sel_hi:[1,1]
	v_pk_mul_f32 v[32:33], v[32:33], v[166:167] op_sel_hi:[1,0]
	v_pk_mul_f32 v[34:35], v[34:35], v[166:167] op_sel_hi:[1,0]
	v_pk_mul_f32 v[36:37], v[36:37], v[166:167] op_sel:[0,1] op_sel_hi:[1,1]
	v_pk_mul_f32 v[38:39], v[38:39], v[166:167] op_sel:[0,1] op_sel_hi:[1,1]
	v_pk_mul_f32 v[40:41], v[40:41], v[168:169] op_sel_hi:[1,0]
	v_pk_mul_f32 v[42:43], v[42:43], v[168:169] op_sel_hi:[1,0]
	v_pk_mul_f32 v[44:45], v[44:45], v[168:169] op_sel:[0,1] op_sel_hi:[1,1]
	v_pk_mul_f32 v[46:47], v[46:47], v[168:169] op_sel:[0,1] op_sel_hi:[1,1]
	v_pk_mul_f32 v[48:49], v[48:49], v[170:171] op_sel_hi:[1,0]
	v_pk_mul_f32 v[50:51], v[50:51], v[170:171] op_sel_hi:[1,0]
	v_pk_mul_f32 v[52:53], v[52:53], v[170:171] op_sel:[0,1] op_sel_hi:[1,1]
	v_pk_mul_f32 v[54:55], v[54:55], v[170:171] op_sel:[0,1] op_sel_hi:[1,1]
	v_pk_mul_f32 v[56:57], v[56:57], v[172:173] op_sel_hi:[1,0]
	v_pk_mul_f32 v[58:59], v[58:59], v[172:173] op_sel_hi:[1,0]
	v_pk_mul_f32 v[60:61], v[60:61], v[172:173] op_sel:[0,1] op_sel_hi:[1,1]
	v_pk_mul_f32 v[62:63], v[62:63], v[172:173] op_sel:[0,1] op_sel_hi:[1,1]
	v_permlane16_swap_b32_e32 v0, v1
	v_permlane16_swap_b32_e32 v2, v3
	v_permlane16_swap_b32_e32 v4, v5
	v_permlane16_swap_b32_e32 v6, v7
	v_permlane16_swap_b32_e32 v8, v9
	v_permlane16_swap_b32_e32 v10, v11
	v_permlane16_swap_b32_e32 v12, v13
	v_permlane16_swap_b32_e32 v14, v15
	v_permlane16_swap_b32_e32 v16, v17
	v_permlane16_swap_b32_e32 v18, v19
	v_permlane16_swap_b32_e32 v20, v21
	v_permlane16_swap_b32_e32 v22, v23
	v_permlane16_swap_b32_e32 v24, v25
	v_permlane16_swap_b32_e32 v26, v27
	v_permlane16_swap_b32_e32 v28, v29
	v_permlane16_swap_b32_e32 v30, v31
	v_permlane16_swap_b32_e32 v32, v33
	v_permlane16_swap_b32_e32 v34, v35
	v_permlane16_swap_b32_e32 v36, v37
	v_permlane16_swap_b32_e32 v38, v39
	v_permlane16_swap_b32_e32 v40, v41
	v_permlane16_swap_b32_e32 v42, v43
	v_permlane16_swap_b32_e32 v44, v45
	v_permlane16_swap_b32_e32 v46, v47
	v_permlane16_swap_b32_e32 v48, v49
	v_permlane16_swap_b32_e32 v50, v51
	v_permlane16_swap_b32_e32 v52, v53
	v_permlane16_swap_b32_e32 v54, v55
	v_permlane16_swap_b32_e32 v56, v57
	v_permlane16_swap_b32_e32 v58, v59
	v_permlane16_swap_b32_e32 v60, v61
	v_permlane16_swap_b32_e32 v62, v63
	v_permlane32_swap_b32_e32 v0, v2
	v_permlane32_swap_b32_e32 v1, v3
	v_permlane32_swap_b32_e32 v4, v6
	v_permlane32_swap_b32_e32 v5, v7
	v_permlane32_swap_b32_e32 v8, v10
	v_permlane32_swap_b32_e32 v9, v11
	v_permlane32_swap_b32_e32 v12, v14
	v_permlane32_swap_b32_e32 v13, v15
	v_permlane32_swap_b32_e32 v16, v18
	v_permlane32_swap_b32_e32 v17, v19
	v_permlane32_swap_b32_e32 v20, v22
	v_permlane32_swap_b32_e32 v21, v23
	v_permlane32_swap_b32_e32 v24, v26
	v_permlane32_swap_b32_e32 v25, v27
	v_permlane32_swap_b32_e32 v28, v30
	v_permlane32_swap_b32_e32 v29, v31
	v_permlane32_swap_b32_e32 v32, v34
	v_permlane32_swap_b32_e32 v33, v35
	v_permlane32_swap_b32_e32 v36, v38
	v_permlane32_swap_b32_e32 v37, v39
	v_permlane32_swap_b32_e32 v40, v42
	v_permlane32_swap_b32_e32 v41, v43
	v_permlane32_swap_b32_e32 v44, v46
	v_permlane32_swap_b32_e32 v45, v47
	v_permlane32_swap_b32_e32 v48, v50
	v_permlane32_swap_b32_e32 v49, v51
	v_permlane32_swap_b32_e32 v52, v54
	v_permlane32_swap_b32_e32 v53, v55
	v_permlane32_swap_b32_e32 v56, v58
	v_permlane32_swap_b32_e32 v57, v59
	v_permlane32_swap_b32_e32 v60, v62
	v_permlane32_swap_b32_e32 v61, v63
	v_cvt_pk_bf16_f32 v206, v0, v1
	v_cvt_pk_bf16_f32 v207, v2, v3
	v_cvt_pk_bf16_f32 v208, v4, v5
	v_cvt_pk_bf16_f32 v209, v6, v7
	v_cvt_pk_bf16_f32 v210, v8, v9
	v_cvt_pk_bf16_f32 v211, v10, v11
	v_cvt_pk_bf16_f32 v212, v12, v13
	v_cvt_pk_bf16_f32 v213, v14, v15
	v_cvt_pk_bf16_f32 v214, v16, v17
; #define PG8_LAS __attribute__((address_space(3)))
; __device__ __forceinline__ unsigned cvt_pk_bf16(float lo, float hi) { unsigned r; asm volatile("v_cvt_pk_bf16_f32 %0, %1, %2" : "=v"(r) : "v"(lo), "v"(hi)); return r; }
; #define lane lane_id()
; __device__ __forceinline__ void conv_store4_lds(int K, int N, bf16_t* __restrict__ WT, int item, int lane, const float* __restrict__ gk, const f32x4 (&x)[16], PG8_LAS unsigned char* sw) {
;     const int nblk = N / 64, k0 = 64 * (item / nblk), n0 = 64 * (item % nblk);
;     const int nq = lane & 15, r = lane >> 4;
;     u32x4 o[8];
; #pragma unroll
;     for (int kc = 0; kc < 8; ++kc) {
;         float g[8];
; #pragma unroll
;         for (int j = 0; j < 8; ++j) g[j] = gk ? gk[k0 + 8 * kc + j] : 1.0f;
;         const f32x4 lo = x[2 * kc], hi = x[2 * kc + 1];
;         o[kc].x = cvt_pk_bf16(lo[0] * g[0], lo[1] * g[1]); o[kc].y = cvt_pk_bf16(lo[2] * g[2], lo[3] * g[3]);
;         o[kc].z = cvt_pk_bf16(hi[0] * g[4], hi[1] * g[5]); o[kc].w = cvt_pk_bf16(hi[2] * g[6], hi[3] * g[7]);
;     }
; #pragma unroll
;     for (int q = 0; q < 4; ++q) {
;         if ((nq >> 2) == q) {
;             PG8_LAS u32x4* wp = (PG8_LAS u32x4*)(sw + (4 * (nq & 3) + r) * 128);
; #pragma unroll
;             for (int kc = 0; kc < 8; ++kc) wp[kc] = o[kc];
;         }
;         asm volatile("s_waitcnt lgkmcnt(0)" ::: "memory");
; #pragma unroll
;         for (int h = 0; h < 2; ++h) { const int rl = (lane >> 3) + 8 * h;
;             const u32x4 v = *(const PG8_LAS u32x4*)(sw + rl * 128 + (lane & 7) * 16);
;             __builtin_nontemporal_store(v, (u32x4*)(WT + (size_t)(n0 + 16 * q + rl) * K + k0 + 8 * (lane & 7))); }
;         asm volatile("s_waitcnt lgkmcnt(0)" ::: "memory");
;     }
; }
;     __device__ __forceinline__ void done(const Unit&) const {
;     ...
;         for (int it = gw; it < I2; it += ngw) {
;             const bool two = it < I4;
;             conv_load4(w2, DM, it, ln, va); if (two) conv_load4(w4, DM, it, ln, vb);
	v_cvt_pk_bf16_f32 v215, v18, v19
	v_cvt_pk_bf16_f32 v216, v20, v21
	v_cvt_pk_bf16_f32 v217, v22, v23
	v_cvt_pk_bf16_f32 v218, v24, v25
	v_cvt_pk_bf16_f32 v219, v26, v27
	v_cvt_pk_bf16_f32 v220, v28, v29
	v_cvt_pk_bf16_f32 v221, v30, v31
	v_cvt_pk_bf16_f32 v222, v32, v33
	v_cvt_pk_bf16_f32 v223, v34, v35
	v_cvt_pk_bf16_f32 v224, v36, v37
	v_cvt_pk_bf16_f32 v225, v38, v39
	v_cvt_pk_bf16_f32 v226, v40, v41
	v_cvt_pk_bf16_f32 v227, v42, v43
	v_cvt_pk_bf16_f32 v228, v44, v45
	v_cvt_pk_bf16_f32 v229, v46, v47
	v_cvt_pk_bf16_f32 v230, v48, v49
	v_cvt_pk_bf16_f32 v231, v50, v51
	v_cvt_pk_bf16_f32 v232, v52, v53
	v_cvt_pk_bf16_f32 v233, v54, v55
	v_cvt_pk_bf16_f32 v234, v56, v57
	v_cvt_pk_bf16_f32 v235, v58, v59
	v_cvt_pk_bf16_f32 v236, v60, v61
	v_cvt_pk_bf16_f32 v237, v62, v63
	s_mov_b32 s37, s96
	s_lshr_b32 s18, s37, 5
	s_lshl_b32 s18, s18, 6
	s_and_b32 s19, s37, 31
	s_lshl_b32 s19, s19, 6
	s_lshl_b32 s49, s19, 13
	s_lshl_b32 s50, s18, 1
	s_add_i32 s39, s49, s50
	v_add_u32_e32 v240, s18, v153
	v_mov_b32_e32 v241, 0
	v_lshlrev_b64 v[240:241], 13, v[240:241]
	s_lshl_b32 s100, s19, 2
	s_mov_b32 s101, 0
	v_lshl_add_u64 v[238:239], s[100:101], 0, v[140:141]
	v_lshl_add_u64 v[238:239], v[238:239], 0, v[240:241]
	s_mov_b32 s46, 0x8000
	s_mov_b32 s47, 0
	global_load_dwordx4 v[0:3], v[238:239], off nt
	v_lshl_add_u64 v[238:239], v[238:239], 0, s[46:47]
	global_load_dwordx4 v[4:7], v[238:239], off nt
	v_lshl_add_u64 v[238:239], v[238:239], 0, s[46:47]
	global_load_dwordx4 v[8:11], v[238:239], off nt
	v_lshl_add_u64 v[238:239], v[238:239], 0, s[46:47]
	global_load_dwordx4 v[12:15], v[238:239], off nt
	v_lshl_add_u64 v[238:239], v[238:239], 0, s[46:47]
	global_load_dwordx4 v[16:19], v[238:239], off nt
	v_lshl_add_u64 v[238:239], v[238:239], 0, s[46:47]
	global_load_dwordx4 v[20:23], v[238:239], off nt
	v_lshl_add_u64 v[238:239], v[238:239], 0, s[46:47]
	global_load_dwordx4 v[24:27], v[238:239], off nt
	v_lshl_add_u64 v[238:239], v[238:239], 0, s[46:47]
	global_load_dwordx4 v[28:31], v[238:239], off nt
	v_lshl_add_u64 v[238:239], v[238:239], 0, s[46:47]
	global_load_dwordx4 v[32:35], v[238:239], off nt
	v_lshl_add_u64 v[238:239], v[238:239], 0, s[46:47]
	global_load_dwordx4 v[36:39], v[238:239], off nt
	v_lshl_add_u64 v[238:239], v[238:239], 0, s[46:47]
	global_load_dwordx4 v[40:43], v[238:239], off nt
	v_lshl_add_u64 v[238:239], v[238:239], 0, s[46:47]
	global_load_dwordx4 v[44:47], v[238:239], off nt
	v_lshl_add_u64 v[238:239], v[238:239], 0, s[46:47]
	global_load_dwordx4 v[48:51], v[238:239], off nt
	v_lshl_add_u64 v[238:239], v[238:239], 0, s[46:47]
	global_load_dwordx4 v[52:55], v[238:239], off nt
	v_lshl_add_u64 v[238:239], v[238:239], 0, s[46:47]
	global_load_dwordx4 v[56:59], v[238:239], off nt
	v_lshl_add_u64 v[238:239], v[238:239], 0, s[46:47]
	global_load_dwordx4 v[60:63], v[238:239], off nt
	s_mov_b32 s44, s24
	s_mov_b32 s45, 0
	s_mov_b32 s100, 0x8000
	s_mov_b32 s101, 0
	v_lshlrev_b32_e32 v170, 12, v197
	v_mov_b32_e32 v171, 0
	s_and_saveexec_b64 s[22:23], s[8:9]
	ds_write_b128 v196, v[206:209]
	ds_write_b128 v196, v[210:213] offset:16
	ds_write_b128 v196, v[214:217] offset:32
	ds_write_b128 v196, v[218:221] offset:48
	ds_write_b128 v196, v[222:225] offset:64
	ds_write_b128 v196, v[226:229] offset:80
	ds_write_b128 v196, v[230:233] offset:96
	ds_write_b128 v196, v[234:237] offset:112
	s_mov_b64 exec, s[22:23]
	s_waitcnt lgkmcnt(0)
	ds_read_b128 v[158:161], v246
	ds_read_b128 v[162:165], v247
	v_lshl_add_u64 v[166:167], s[44:45], 0, v[138:139]
	v_lshl_add_u64 v[166:167], v[166:167], 0, v[170:171]
	v_lshl_add_u64 v[168:169], v[166:167], 0, s[100:101]
	s_waitcnt lgkmcnt(0)
	global_store_dwordx4 v[166:167], v[158:161], off nt
	global_store_dwordx4 v[168:169], v[162:165], off nt
	s_add_u32 s44, s44, 0x10000
	s_and_saveexec_b64 s[22:23], s[10:11]
	ds_write_b128 v196, v[206:209]
	ds_write_b128 v196, v[210:213] offset:16
	ds_write_b128 v196, v[214:217] offset:32
	ds_write_b128 v196, v[218:221] offset:48
	ds_write_b128 v196, v[222:225] offset:64
	ds_write_b128 v196, v[226:229] offset:80
	ds_write_b128 v196, v[230:233] offset:96
	ds_write_b128 v196, v[234:237] offset:112
	s_mov_b64 exec, s[22:23]
	s_waitcnt lgkmcnt(0)
	ds_read_b128 v[238:241], v246
	ds_read_b128 v[242:245], v247
	v_lshl_add_u64 v[166:167], s[44:45], 0, v[138:139]
	v_lshl_add_u64 v[166:167], v[166:167], 0, v[170:171]
	v_lshl_add_u64 v[168:169], v[166:167], 0, s[100:101]
	s_waitcnt lgkmcnt(0)
	global_store_dwordx4 v[166:167], v[238:241], off nt
	global_store_dwordx4 v[168:169], v[242:245], off nt
	s_add_u32 s44, s44, 0x10000
	s_and_saveexec_b64 s[22:23], s[12:13]
	ds_write_b128 v196, v[206:209]
	ds_write_b128 v196, v[210:213] offset:16
	ds_write_b128 v196, v[214:217] offset:32
	ds_write_b128 v196, v[218:221] offset:48
	ds_write_b128 v196, v[222:225] offset:64
	ds_write_b128 v196, v[226:229] offset:80
	ds_write_b128 v196, v[230:233] offset:96
	ds_write_b128 v196, v[234:237] offset:112
	s_mov_b64 exec, s[22:23]
	s_waitcnt lgkmcnt(0)
	ds_read_b128 v[158:161], v246
	ds_read_b128 v[162:165], v247
	v_lshl_add_u64 v[166:167], s[44:45], 0, v[138:139]
	v_lshl_add_u64 v[166:167], v[166:167], 0, v[170:171]
	v_lshl_add_u64 v[168:169], v[166:167], 0, s[100:101]
	s_waitcnt lgkmcnt(0)
	global_store_dwordx4 v[166:167], v[158:161], off nt
	global_store_dwordx4 v[168:169], v[162:165], off nt
	s_add_u32 s44, s44, 0x10000
	s_and_saveexec_b64 s[22:23], s[14:15]
	ds_write_b128 v196, v[206:209]
	ds_write_b128 v196, v[210:213] offset:16
	ds_write_b128 v196, v[214:217] offset:32
	ds_write_b128 v196, v[218:221] offset:48
	ds_write_b128 v196, v[222:225] offset:64
	ds_write_b128 v196, v[226:229] offset:80
	ds_write_b128 v196, v[230:233] offset:96
	ds_write_b128 v196, v[234:237] offset:112
	s_mov_b64 exec, s[22:23]
	s_waitcnt lgkmcnt(0)
; #define PG8_LAS __attribute__((address_space(3)))
; #define lane lane_id()
; __device__ __forceinline__ void conv_store4_lds(int K, int N, bf16_t* __restrict__ WT, int item, int lane, const float* __restrict__ gk, const f32x4 (&x)[16], PG8_LAS unsigned char* sw) {
;     ...
;     for (int q = 0; q < 4; ++q) {
;         if ((nq >> 2) == q) {
;             PG8_LAS u32x4* wp = (PG8_LAS u32x4*)(sw + (4 * (nq & 3) + r) * 128);
; #pragma unroll
;             for (int kc = 0; kc < 8; ++kc) wp[kc] = o[kc];
;         }
;         asm volatile("s_waitcnt lgkmcnt(0)" ::: "memory");
; #pragma unroll
;         for (int h = 0; h < 2; ++h) { const int rl = (lane >> 3) + 8 * h;
;             const u32x4 v = *(const PG8_LAS u32x4*)(sw + rl * 128 + (lane & 7) * 16);
;             __builtin_nontemporal_store(v, (u32x4*)(WT + (size_t)(n0 + 16 * q + rl) * K + k0 + 8 * (lane & 7))); }
;         asm volatile("s_waitcnt lgkmcnt(0)" ::: "memory");
;     }
; }
;     __device__ __forceinline__ void done(const Unit&) const {
;     ...
;             conv_load4(w3, 4 * DM, it, ln, va); if (two) conv_load4(w3, 4 * DM, it + ngw, ln, vb);
;             conv_xpose(va, ln); if (two) conv_xpose(vb, ln);
;             conv_store4_lds(DM, 4 * DM, t3, it, ln, g1, va, sw); if (two) conv_store4_lds(DM, 4 * DM, t3, it + ngw, ln, g1, vb, sw);
	ds_read_b128 v[238:241], v246
	ds_read_b128 v[242:245], v247
	v_lshl_add_u64 v[166:167], s[44:45], 0, v[138:139]
	v_lshl_add_u64 v[166:167], v[166:167], 0, v[170:171]
	v_lshl_add_u64 v[168:169], v[166:167], 0, s[100:101]
	s_waitcnt lgkmcnt(0)
	global_store_dwordx4 v[166:167], v[238:241], off nt
	global_store_dwordx4 v[168:169], v[242:245], off nt
	s_waitcnt vmcnt(24)
	v_pk_mul_f32 v[64:65], v[64:65], v[174:175] op_sel_hi:[1,0]
	v_pk_mul_f32 v[66:67], v[66:67], v[174:175] op_sel_hi:[1,0]
	v_pk_mul_f32 v[68:69], v[68:69], v[174:175] op_sel:[0,1] op_sel_hi:[1,1]
	v_pk_mul_f32 v[70:71], v[70:71], v[174:175] op_sel:[0,1] op_sel_hi:[1,1]
	v_pk_mul_f32 v[72:73], v[72:73], v[176:177] op_sel_hi:[1,0]
	v_pk_mul_f32 v[74:75], v[74:75], v[176:177] op_sel_hi:[1,0]
	v_pk_mul_f32 v[76:77], v[76:77], v[176:177] op_sel:[0,1] op_sel_hi:[1,1]
	v_pk_mul_f32 v[78:79], v[78:79], v[176:177] op_sel:[0,1] op_sel_hi:[1,1]
	v_pk_mul_f32 v[80:81], v[80:81], v[178:179] op_sel_hi:[1,0]
	v_pk_mul_f32 v[82:83], v[82:83], v[178:179] op_sel_hi:[1,0]
	v_pk_mul_f32 v[84:85], v[84:85], v[178:179] op_sel:[0,1] op_sel_hi:[1,1]
	v_pk_mul_f32 v[86:87], v[86:87], v[178:179] op_sel:[0,1] op_sel_hi:[1,1]
	v_pk_mul_f32 v[88:89], v[88:89], v[180:181] op_sel_hi:[1,0]
	v_pk_mul_f32 v[90:91], v[90:91], v[180:181] op_sel_hi:[1,0]
	v_pk_mul_f32 v[92:93], v[92:93], v[180:181] op_sel:[0,1] op_sel_hi:[1,1]
	v_pk_mul_f32 v[94:95], v[94:95], v[180:181] op_sel:[0,1] op_sel_hi:[1,1]
	v_pk_mul_f32 v[96:97], v[96:97], v[182:183] op_sel_hi:[1,0]
	v_pk_mul_f32 v[98:99], v[98:99], v[182:183] op_sel_hi:[1,0]
	v_pk_mul_f32 v[100:101], v[100:101], v[182:183] op_sel:[0,1] op_sel_hi:[1,1]
	v_pk_mul_f32 v[102:103], v[102:103], v[182:183] op_sel:[0,1] op_sel_hi:[1,1]
	v_pk_mul_f32 v[104:105], v[104:105], v[184:185] op_sel_hi:[1,0]
	v_pk_mul_f32 v[106:107], v[106:107], v[184:185] op_sel_hi:[1,0]
	v_pk_mul_f32 v[108:109], v[108:109], v[184:185] op_sel:[0,1] op_sel_hi:[1,1]
	v_pk_mul_f32 v[110:111], v[110:111], v[184:185] op_sel:[0,1] op_sel_hi:[1,1]
	v_pk_mul_f32 v[112:113], v[112:113], v[186:187] op_sel_hi:[1,0]
	v_pk_mul_f32 v[114:115], v[114:115], v[186:187] op_sel_hi:[1,0]
	v_pk_mul_f32 v[116:117], v[116:117], v[186:187] op_sel:[0,1] op_sel_hi:[1,1]
	v_pk_mul_f32 v[118:119], v[118:119], v[186:187] op_sel:[0,1] op_sel_hi:[1,1]
	v_pk_mul_f32 v[120:121], v[120:121], v[188:189] op_sel_hi:[1,0]
	v_pk_mul_f32 v[122:123], v[122:123], v[188:189] op_sel_hi:[1,0]
	v_pk_mul_f32 v[124:125], v[124:125], v[188:189] op_sel:[0,1] op_sel_hi:[1,1]
	v_pk_mul_f32 v[126:127], v[126:127], v[188:189] op_sel:[0,1] op_sel_hi:[1,1]
	v_permlane16_swap_b32_e32 v64, v65
	v_permlane16_swap_b32_e32 v66, v67
	v_permlane16_swap_b32_e32 v68, v69
	v_permlane16_swap_b32_e32 v70, v71
	v_permlane16_swap_b32_e32 v72, v73
	v_permlane16_swap_b32_e32 v74, v75
	v_permlane16_swap_b32_e32 v76, v77
	v_permlane16_swap_b32_e32 v78, v79
	v_permlane16_swap_b32_e32 v80, v81
	v_permlane16_swap_b32_e32 v82, v83
	v_permlane16_swap_b32_e32 v84, v85
	v_permlane16_swap_b32_e32 v86, v87
	v_permlane16_swap_b32_e32 v88, v89
	v_permlane16_swap_b32_e32 v90, v91
	v_permlane16_swap_b32_e32 v92, v93
	v_permlane16_swap_b32_e32 v94, v95
	v_permlane16_swap_b32_e32 v96, v97
	v_permlane16_swap_b32_e32 v98, v99
	v_permlane16_swap_b32_e32 v100, v101
	v_permlane16_swap_b32_e32 v102, v103
	v_permlane16_swap_b32_e32 v104, v105
	v_permlane16_swap_b32_e32 v106, v107
	v_permlane16_swap_b32_e32 v108, v109
	v_permlane16_swap_b32_e32 v110, v111
	v_permlane16_swap_b32_e32 v112, v113
	v_permlane16_swap_b32_e32 v114, v115
	v_permlane16_swap_b32_e32 v116, v117
	v_permlane16_swap_b32_e32 v118, v119
	v_permlane16_swap_b32_e32 v120, v121
	v_permlane16_swap_b32_e32 v122, v123
	v_permlane16_swap_b32_e32 v124, v125
	v_permlane16_swap_b32_e32 v126, v127
	v_permlane32_swap_b32_e32 v64, v66
	v_permlane32_swap_b32_e32 v65, v67
	v_permlane32_swap_b32_e32 v68, v70
	v_permlane32_swap_b32_e32 v69, v71
	v_permlane32_swap_b32_e32 v72, v74
	v_permlane32_swap_b32_e32 v73, v75
	v_permlane32_swap_b32_e32 v76, v78
	v_permlane32_swap_b32_e32 v77, v79
	v_permlane32_swap_b32_e32 v80, v82
	v_permlane32_swap_b32_e32 v81, v83
	v_permlane32_swap_b32_e32 v84, v86
	v_permlane32_swap_b32_e32 v85, v87
	v_permlane32_swap_b32_e32 v88, v90
	v_permlane32_swap_b32_e32 v89, v91
	v_permlane32_swap_b32_e32 v92, v94
	v_permlane32_swap_b32_e32 v93, v95
	v_permlane32_swap_b32_e32 v96, v98
	v_permlane32_swap_b32_e32 v97, v99
	v_permlane32_swap_b32_e32 v100, v102
	v_permlane32_swap_b32_e32 v101, v103
	v_permlane32_swap_b32_e32 v104, v106
	v_permlane32_swap_b32_e32 v105, v107
	v_permlane32_swap_b32_e32 v108, v110
	v_permlane32_swap_b32_e32 v109, v111
	v_permlane32_swap_b32_e32 v112, v114
	v_permlane32_swap_b32_e32 v113, v115
	v_permlane32_swap_b32_e32 v116, v118
	v_permlane32_swap_b32_e32 v117, v119
	v_permlane32_swap_b32_e32 v120, v122
	v_permlane32_swap_b32_e32 v121, v123
	v_permlane32_swap_b32_e32 v124, v126
	v_permlane32_swap_b32_e32 v125, v127
	v_cvt_pk_bf16_f32 v206, v64, v65
	v_cvt_pk_bf16_f32 v207, v66, v67
	v_cvt_pk_bf16_f32 v208, v68, v69
	v_cvt_pk_bf16_f32 v209, v70, v71
	v_cvt_pk_bf16_f32 v210, v72, v73
	v_cvt_pk_bf16_f32 v211, v74, v75
	v_cvt_pk_bf16_f32 v212, v76, v77
	v_cvt_pk_bf16_f32 v213, v78, v79
	v_cvt_pk_bf16_f32 v214, v80, v81
	v_cvt_pk_bf16_f32 v215, v82, v83
	v_cvt_pk_bf16_f32 v216, v84, v85
	v_cvt_pk_bf16_f32 v217, v86, v87
	v_cvt_pk_bf16_f32 v218, v88, v89
	v_cvt_pk_bf16_f32 v219, v90, v91
	v_cvt_pk_bf16_f32 v220, v92, v93
	v_cvt_pk_bf16_f32 v221, v94, v95
	v_cvt_pk_bf16_f32 v222, v96, v97
	v_cvt_pk_bf16_f32 v223, v98, v99
	v_cvt_pk_bf16_f32 v224, v100, v101
	v_cvt_pk_bf16_f32 v225, v102, v103
	v_cvt_pk_bf16_f32 v226, v104, v105
	v_cvt_pk_bf16_f32 v227, v106, v107
	v_cvt_pk_bf16_f32 v228, v108, v109
	v_cvt_pk_bf16_f32 v229, v110, v111
	v_cvt_pk_bf16_f32 v230, v112, v113
	v_cvt_pk_bf16_f32 v231, v114, v115
	v_cvt_pk_bf16_f32 v232, v116, v117
	v_cvt_pk_bf16_f32 v233, v118, v119
	v_cvt_pk_bf16_f32 v234, v120, v121
	v_cvt_pk_bf16_f32 v235, v122, v123
	v_cvt_pk_bf16_f32 v236, v124, v125
	v_cvt_pk_bf16_f32 v237, v126, v127
	s_cmpk_lt_u32 s96, 0x400
	s_cbranch_scc0 .Lhk_noD1
; #define lane lane_id()
; __device__ __forceinline__ void conv_load4(const float* __restrict__ W, int N, int item, int lane, f32x4 (&x)[16]) {
;     const int nblk = N / 64, k0 = 64 * (item / nblk), n0 = 64 * (item % nblk);
; #pragma unroll
;     for (int i = 0; i < 16; ++i) x[i] = __builtin_nontemporal_load((const f32x4*)(W + (size_t)(k0 + 4 * i + (lane >> 4)) * N + n0 + 4 * (lane & 15)));
; }
;     __device__ __forceinline__ void done(const Unit&) const {
;     ...
;         for (int it = gw; it < I2; it += ngw) {
;             const bool two = it < I4;
;             conv_load4(w2, DM, it, ln, va); if (two) conv_load4(w4, DM, it, ln, vb);
	s_mov_b32 s37, s96
	s_lshr_b32 s18, s37, 5
	s_lshl_b32 s18, s18, 6
	s_and_b32 s19, s37, 31
	s_lshl_b32 s19, s19, 6
	s_lshl_b32 s49, s19, 12
	s_lshl_b32 s50, s18, 1
	s_add_i32 s48, s49, s50
	v_add_u32_e32 v240, s18, v153
	v_mov_b32_e32 v241, 0
	v_lshlrev_b64 v[240:241], 13, v[240:241]
	s_lshl_b32 s100, s19, 2
	s_mov_b32 s101, 0
	v_lshl_add_u64 v[238:239], s[100:101], 0, v[142:143]
	v_lshl_add_u64 v[238:239], v[238:239], 0, v[240:241]
	s_mov_b32 s46, 0x8000
	s_mov_b32 s47, 0
	global_load_dwordx4 v[64:67], v[238:239], off nt
	v_lshl_add_u64 v[238:239], v[238:239], 0, s[46:47]
	global_load_dwordx4 v[68:71], v[238:239], off nt
	v_lshl_add_u64 v[238:239], v[238:239], 0, s[46:47]
	global_load_dwordx4 v[72:75], v[238:239], off nt
	v_lshl_add_u64 v[238:239], v[238:239], 0, s[46:47]
	global_load_dwordx4 v[76:79], v[238:239], off nt
	v_lshl_add_u64 v[238:239], v[238:239], 0, s[46:47]
	global_load_dwordx4 v[80:83], v[238:239], off nt
	v_lshl_add_u64 v[238:239], v[238:239], 0, s[46:47]
	global_load_dwordx4 v[84:87], v[238:239], off nt
	v_lshl_add_u64 v[238:239], v[238:239], 0, s[46:47]
	global_load_dwordx4 v[88:91], v[238:239], off nt
	v_lshl_add_u64 v[238:239], v[238:239], 0, s[46:47]
	global_load_dwordx4 v[92:95], v[238:239], off nt
	v_lshl_add_u64 v[238:239], v[238:239], 0, s[46:47]
	global_load_dwordx4 v[96:99], v[238:239], off nt
	v_lshl_add_u64 v[238:239], v[238:239], 0, s[46:47]
	global_load_dwordx4 v[100:103], v[238:239], off nt
	v_lshl_add_u64 v[238:239], v[238:239], 0, s[46:47]
	global_load_dwordx4 v[104:107], v[238:239], off nt
	v_lshl_add_u64 v[238:239], v[238:239], 0, s[46:47]
	global_load_dwordx4 v[108:111], v[238:239], off nt
	v_lshl_add_u64 v[238:239], v[238:239], 0, s[46:47]
	global_load_dwordx4 v[112:115], v[238:239], off nt
	v_lshl_add_u64 v[238:239], v[238:239], 0, s[46:47]
	global_load_dwordx4 v[116:119], v[238:239], off nt
	v_lshl_add_u64 v[238:239], v[238:239], 0, s[46:47]
	global_load_dwordx4 v[120:123], v[238:239], off nt
	v_lshl_add_u64 v[238:239], v[238:239], 0, s[46:47]
	global_load_dwordx4 v[124:127], v[238:239], off nt
